# SSD local item third conv (C): per 8-channel group straight path with tap-batched loads when all taps in range
# speedup vs baseline: 1.0001x; 1.0001x over previous
.Lssdx_tail:
	s_waitcnt vmcnt(2)
	v_mul_f32_e32 v32, 0xbfb8aa3b, v20
	v_mul_f32_e32 v33, 0xbfb8aa3b, v21
	v_exp_f32_e32 v32, v32
	v_exp_f32_e32 v33, v33
	v_lshrrev_b32_e32 v67, 5, v38
	v_and_b32_e32 v68, 31, v66
	v_add_f32_e32 v32, 1.0, v32
	v_add_f32_e32 v33, 1.0, v33
	v_rcp_f32_e32 v32, v32
	v_rcp_f32_e32 v33, v33
	v_lshlrev_b32_e32 v70, 3, v67
	v_pk_mul_f32 v[20:21], v[20:21], v[32:33]
	v_mul_f32_e32 v32, 0xbfb8aa3b, v22
	v_mul_f32_e32 v33, 0xbfb8aa3b, v23
	v_exp_f32_e32 v32, v32
	v_exp_f32_e32 v33, v33
	v_add_f32_e32 v32, 1.0, v32
	v_add_f32_e32 v33, 1.0, v33
	v_rcp_f32_e32 v32, v32
	v_rcp_f32_e32 v33, v33
	s_nop 0
	v_pk_mul_f32 v[22:23], v[22:23], v[32:33]
	v_mul_f32_e32 v32, 0xbfb8aa3b, v16
	v_mul_f32_e32 v33, 0xbfb8aa3b, v17
	v_exp_f32_e32 v32, v32
	v_exp_f32_e32 v33, v33
	v_add_f32_e32 v32, 1.0, v32
	v_add_f32_e32 v33, 1.0, v33
	v_rcp_f32_e32 v32, v32
	v_rcp_f32_e32 v33, v33
	s_nop 0
	v_pk_mul_f32 v[16:17], v[16:17], v[32:33]
	v_mul_f32_e32 v32, 0xbfb8aa3b, v18
	v_mul_f32_e32 v33, 0xbfb8aa3b, v19
	v_exp_f32_e32 v32, v32
	v_exp_f32_e32 v33, v33
	v_add_f32_e32 v32, 1.0, v32
	v_add_f32_e32 v33, 1.0, v33
	v_rcp_f32_e32 v32, v32
	v_rcp_f32_e32 v33, v33
	s_nop 0
	v_pk_mul_f32 v[18:19], v[18:19], v[32:33]
	v_mul_f32_e32 v32, 0xbfb8aa3b, v12
	v_mul_f32_e32 v33, 0xbfb8aa3b, v13
	v_exp_f32_e32 v32, v32
	v_exp_f32_e32 v33, v33
	v_add_f32_e32 v32, 1.0, v32
	v_add_f32_e32 v33, 1.0, v33
	v_rcp_f32_e32 v32, v32
	v_rcp_f32_e32 v33, v33
	s_nop 0
	v_pk_mul_f32 v[12:13], v[12:13], v[32:33]
	v_mul_f32_e32 v32, 0xbfb8aa3b, v14
	v_mul_f32_e32 v33, 0xbfb8aa3b, v15
	v_exp_f32_e32 v32, v32
	v_exp_f32_e32 v33, v33
	v_add_f32_e32 v32, 1.0, v32
	v_add_f32_e32 v33, 1.0, v33
	v_rcp_f32_e32 v32, v32
	v_rcp_f32_e32 v33, v33
	s_nop 0
	v_pk_mul_f32 v[14:15], v[14:15], v[32:33]
	v_mul_f32_e32 v32, 0xbfb8aa3b, v8
	v_mul_f32_e32 v33, 0xbfb8aa3b, v9
	v_exp_f32_e32 v32, v32
	v_exp_f32_e32 v33, v33
	v_add_f32_e32 v32, 1.0, v32
	v_add_f32_e32 v33, 1.0, v33
	v_rcp_f32_e32 v32, v32
	v_rcp_f32_e32 v33, v33
	s_nop 0
	v_pk_mul_f32 v[8:9], v[8:9], v[32:33]
	v_mul_f32_e32 v32, 0xbfb8aa3b, v10
	v_mul_f32_e32 v33, 0xbfb8aa3b, v11
	v_exp_f32_e32 v32, v32
	v_exp_f32_e32 v33, v33
	v_add_f32_e32 v32, 1.0, v32
	v_add_f32_e32 v33, 1.0, v33
	v_rcp_f32_e32 v32, v32
	v_rcp_f32_e32 v33, v33
	s_nop 0
	v_pk_mul_f32 v[10:11], v[10:11], v[32:33]
	v_mul_f32_e32 v32, 0xbfb8aa3b, v4
	v_mul_f32_e32 v33, 0xbfb8aa3b, v5
	v_exp_f32_e32 v32, v32
	v_exp_f32_e32 v33, v33
	v_add_f32_e32 v32, 1.0, v32
	v_add_f32_e32 v33, 1.0, v33
	v_rcp_f32_e32 v32, v32
	v_rcp_f32_e32 v33, v33
	s_nop 0
	v_pk_mul_f32 v[4:5], v[4:5], v[32:33]
	v_mul_f32_e32 v32, 0xbfb8aa3b, v6
	v_mul_f32_e32 v33, 0xbfb8aa3b, v7
	v_exp_f32_e32 v32, v32
	v_exp_f32_e32 v33, v33
	v_add_f32_e32 v32, 1.0, v32
	v_add_f32_e32 v33, 1.0, v33
	v_rcp_f32_e32 v32, v32
	v_rcp_f32_e32 v33, v33
	s_nop 0
	v_pk_mul_f32 v[6:7], v[6:7], v[32:33]
	v_mul_f32_e32 v32, 0xbfb8aa3b, v0
	v_mul_f32_e32 v33, 0xbfb8aa3b, v1
	v_exp_f32_e32 v32, v32
	v_exp_f32_e32 v33, v33
	v_add_f32_e32 v32, 1.0, v32
	v_add_f32_e32 v33, 1.0, v33
	v_rcp_f32_e32 v32, v32
	v_rcp_f32_e32 v33, v33
	s_nop 0
	v_pk_mul_f32 v[34:35], v[0:1], v[32:33]
	v_mul_f32_e32 v0, 0xbfb8aa3b, v2
	v_mul_f32_e32 v1, 0xbfb8aa3b, v3
	v_exp_f32_e32 v0, v0
	v_exp_f32_e32 v1, v1
	v_ashrrev_i32_e32 v32, 6, v66
	v_lshl_or_b32 v69, v32, 5, v68
	v_add_f32_e32 v0, 1.0, v0
	v_add_f32_e32 v1, 1.0, v1
	v_rcp_f32_e32 v0, v0
	v_rcp_f32_e32 v1, v1
	v_add_u32_e32 v64, s86, v69
	v_pk_mul_f32 v[40:41], v[2:3], v[0:1]
	s_waitcnt vmcnt(0)
	v_mul_f32_e32 v0, 0xbfb8aa3b, v28
	v_exp_f32_e32 v0, v0
	s_nop 0
	v_add_f32_e32 v0, 1.0, v0
	v_rcp_f32_e32 v42, v0
	v_mul_f32_e32 v0, 0xbfb8aa3b, v29
	v_exp_f32_e32 v0, v0
	s_nop 0
	v_add_f32_e32 v0, 1.0, v0
	v_rcp_f32_e32 v43, v0
	v_mul_f32_e32 v0, 0xbfb8aa3b, v30
	v_exp_f32_e32 v0, v0
	s_nop 0
	v_add_f32_e32 v0, 1.0, v0
	v_rcp_f32_e32 v44, v0
	v_mul_f32_e32 v0, 0xbfb8aa3b, v31
	v_exp_f32_e32 v0, v0
	s_nop 0
	v_add_f32_e32 v0, 1.0, v0
	v_rcp_f32_e32 v45, v0
	v_mul_f32_e32 v0, 0xbfb8aa3b, v24
	v_exp_f32_e32 v0, v0
	s_nop 0
	v_add_f32_e32 v0, 1.0, v0
	v_rcp_f32_e32 v46, v0
	v_mul_f32_e32 v0, 0xbfb8aa3b, v25
	v_exp_f32_e32 v0, v0
	s_nop 0
	v_add_f32_e32 v0, 1.0, v0
	v_rcp_f32_e32 v47, v0
	v_mul_f32_e32 v0, 0xbfb8aa3b, v26
	v_exp_f32_e32 v0, v0
	s_nop 0
	v_add_f32_e32 v0, 1.0, v0
	v_rcp_f32_e32 v48, v0
	v_mul_f32_e32 v0, 0xbfb8aa3b, v27
	v_exp_f32_e32 v0, v0
	s_nop 0
	v_add_f32_e32 v0, 1.0, v0
	v_rcp_f32_e32 v49, v0
	v_lshl_add_u32 v0, v39, 2, s89
	ds_read_b32 v38, v0 offset:33280
	s_waitcnt lgkmcnt(0)
	v_pk_mul_f32 v[0:1], v[4:5], v[38:39] op_sel_hi:[1,0]
	v_pk_mul_f32 v[2:3], v[6:7], v[38:39] op_sel_hi:[1,0]
	v_cvt_pk_bf16_f32 v0, v0, v1
	v_cvt_pk_bf16_f32 v1, v2, v3
	v_pk_mul_f32 v[2:3], v[34:35], v[38:39] op_sel_hi:[1,0]
	v_pk_mul_f32 v[4:5], v[40:41], v[38:39] op_sel_hi:[1,0]
	v_cvt_pk_bf16_f32 v2, v2, v3
	v_cvt_pk_bf16_f32 v3, v4, v5
	ds_write_b128 v36, v[0:3] offset:16384
	v_pk_mul_f32 v[0:1], v[12:13], v[38:39] op_sel_hi:[1,0]
	v_pk_mul_f32 v[2:3], v[14:15], v[38:39] op_sel_hi:[1,0]
	v_cvt_pk_bf16_f32 v0, v0, v1
	v_cvt_pk_bf16_f32 v1, v2, v3
	v_pk_mul_f32 v[2:3], v[8:9], v[38:39] op_sel_hi:[1,0]
	v_pk_mul_f32 v[4:5], v[10:11], v[38:39] op_sel_hi:[1,0]
	v_cvt_pk_bf16_f32 v2, v2, v3
	v_cvt_pk_bf16_f32 v3, v4, v5
	ds_write_b128 v36, v[0:3] offset:16400
	v_pk_mul_f32 v[0:1], v[20:21], v[38:39] op_sel_hi:[1,0]
	v_pk_mul_f32 v[2:3], v[22:23], v[38:39] op_sel_hi:[1,0]
	v_cvt_pk_bf16_f32 v0, v0, v1
	v_cvt_pk_bf16_f32 v1, v2, v3
	v_pk_mul_f32 v[2:3], v[16:17], v[38:39] op_sel_hi:[1,0]
	v_pk_mul_f32 v[4:5], v[18:19], v[38:39] op_sel_hi:[1,0]
	v_cvt_pk_bf16_f32 v2, v2, v3
	v_cvt_pk_bf16_f32 v3, v4, v5
	ds_write_b128 v36, v[0:3] offset:16416
	v_pk_mul_f32 v[0:1], v[28:29], v[42:43]
	v_pk_mul_f32 v[2:3], v[30:31], v[44:45]
	v_pk_mul_f32 v[0:1], v[38:39], v[0:1] op_sel_hi:[0,1]
	v_pk_mul_f32 v[2:3], v[38:39], v[2:3] op_sel_hi:[0,1]
	v_cvt_pk_bf16_f32 v0, v0, v1
	v_cvt_pk_bf16_f32 v1, v2, v3
	v_pk_mul_f32 v[2:3], v[24:25], v[46:47]
	v_pk_mul_f32 v[4:5], v[26:27], v[48:49]
	v_pk_mul_f32 v[2:3], v[38:39], v[2:3] op_sel_hi:[0,1]
	v_pk_mul_f32 v[4:5], v[38:39], v[4:5] op_sel_hi:[0,1]
	v_cvt_pk_bf16_f32 v2, v2, v3
	v_cvt_pk_bf16_f32 v3, v4, v5
	v_or_b32_e32 v12, s5, v70
	ds_write_b128 v36, v[0:3] offset:16432
	v_add_u32_e32 v0, -3, v64
	v_lshlrev_b32_e32 v168, 2, v12
	v_mad_i64_i32 v[10:11], s[0:1], v0, s93, 0
	global_load_dwordx4 v[0:3], v168, s[74:75] offset:1552
	global_load_dwordx4 v[4:7], v168, s[74:75] offset:1536
	v_lshlrev_b32_e32 v12, 1, v12
	v_mov_b32_e32 v13, v169
	v_add_u32_e32 v20, s68, v69
	v_lshl_add_u64 v[16:17], s[30:31], 0, v[12:13]
	v_cmp_lt_i32_e64 s[6:7], 2, v20
	v_lshl_add_u64 v[8:9], s[14:15], 0, v[168:169]
	v_lshl_add_u64 v[10:11], v[16:17], 0, v[10:11]
	s_cmp_eq_u64 s[6:7], -1
	s_cbranch_scc0 .Lssdc0_slow
	v_cmp_lt_i32_e64 s[8:9], 1, v20
	v_cmp_lt_i32_e64 s[10:11], 0, v20
	v_cmp_lt_i32_e64 s[12:13], -1, v20
	v_add_u32_e32 v12, -2, v64
	v_mad_i64_i32 v[12:13], s[0:1], v12, s93, 0
	v_lshl_add_u64 v[12:13], v[16:17], 0, v[12:13]
	v_add_u32_e32 v14, -1, v64
	v_mad_i64_i32 v[14:15], s[0:1], v14, s93, 0
	v_lshl_add_u64 v[14:15], v[16:17], 0, v[14:15]
	v_mad_i64_i32 v[20:21], s[0:1], v64, s93, 0
	v_lshl_add_u64 v[16:17], v[16:17], 0, v[20:21]
	s_mov_b64 s[0:1], 0x600
	v_lshl_add_u64 v[18:19], v[8:9], 0, s[0:1]
	s_mov_b64 s[0:1], 0x1000
	v_lshl_add_u64 v[140:141], v[8:9], 0, s[0:1]
	global_load_dwordx4 v[92:95], v[10:11], off offset:2304
	global_load_dwordx4 v[96:99], v[12:13], off offset:2304
	global_load_dwordx4 v[100:103], v[14:15], off offset:2304
	global_load_dwordx4 v[104:107], v[16:17], off offset:2304
	global_load_dwordx4 v[108:111], v[8:9], off offset:1536
	global_load_dwordx4 v[112:115], v[8:9], off offset:1552
	global_load_dwordx4 v[116:119], v[8:9], off offset:3584
	global_load_dwordx4 v[120:123], v[8:9], off offset:3600
	global_load_dwordx4 v[124:127], v[140:141], off offset:1536
	global_load_dwordx4 v[128:131], v[140:141], off offset:1552
	global_load_dwordx4 v[132:135], v[140:141], off offset:3584
	global_load_dwordx4 v[136:139], v[140:141], off offset:3600
	s_waitcnt vmcnt(0)
	v_lshlrev_b32_e32 v140, 16, v92
	v_and_b32_e32 v141, 0xffff0000, v92
	v_pk_fma_f32 v[4:5], v[108:109], v[140:141], v[4:5]
	v_lshlrev_b32_e32 v140, 16, v93
	v_and_b32_e32 v141, 0xffff0000, v93
	v_pk_fma_f32 v[6:7], v[110:111], v[140:141], v[6:7]
	v_lshlrev_b32_e32 v140, 16, v94
	v_and_b32_e32 v141, 0xffff0000, v94
	v_pk_fma_f32 v[0:1], v[112:113], v[140:141], v[0:1]
	v_lshlrev_b32_e32 v140, 16, v95
	v_and_b32_e32 v141, 0xffff0000, v95
	v_pk_fma_f32 v[2:3], v[114:115], v[140:141], v[2:3]
	v_lshlrev_b32_e32 v140, 16, v96
	v_and_b32_e32 v141, 0xffff0000, v96
	v_pk_fma_f32 v[4:5], v[116:117], v[140:141], v[4:5]
	v_lshlrev_b32_e32 v140, 16, v97
	v_and_b32_e32 v141, 0xffff0000, v97
	v_pk_fma_f32 v[6:7], v[118:119], v[140:141], v[6:7]
	v_lshlrev_b32_e32 v140, 16, v98
	v_and_b32_e32 v141, 0xffff0000, v98
	v_pk_fma_f32 v[0:1], v[120:121], v[140:141], v[0:1]
	v_lshlrev_b32_e32 v140, 16, v99
	v_and_b32_e32 v141, 0xffff0000, v99
	v_pk_fma_f32 v[2:3], v[122:123], v[140:141], v[2:3]
	v_lshlrev_b32_e32 v140, 16, v100
	v_and_b32_e32 v141, 0xffff0000, v100
	v_pk_fma_f32 v[4:5], v[124:125], v[140:141], v[4:5]
	v_lshlrev_b32_e32 v140, 16, v101
	v_and_b32_e32 v141, 0xffff0000, v101
	v_pk_fma_f32 v[6:7], v[126:127], v[140:141], v[6:7]
	v_lshlrev_b32_e32 v140, 16, v102
	v_and_b32_e32 v141, 0xffff0000, v102
	v_pk_fma_f32 v[0:1], v[128:129], v[140:141], v[0:1]
	v_lshlrev_b32_e32 v140, 16, v103
	v_and_b32_e32 v141, 0xffff0000, v103
	v_pk_fma_f32 v[2:3], v[130:131], v[140:141], v[2:3]
	v_lshlrev_b32_e32 v140, 16, v104
	v_and_b32_e32 v141, 0xffff0000, v104
	v_pk_fma_f32 v[4:5], v[132:133], v[140:141], v[4:5]
	v_lshlrev_b32_e32 v140, 16, v105
	v_and_b32_e32 v141, 0xffff0000, v105
	v_pk_fma_f32 v[6:7], v[134:135], v[140:141], v[6:7]
	v_lshlrev_b32_e32 v140, 16, v106
	v_and_b32_e32 v141, 0xffff0000, v106
	v_pk_fma_f32 v[0:1], v[136:137], v[140:141], v[0:1]
	v_lshlrev_b32_e32 v140, 16, v107
	v_and_b32_e32 v141, 0xffff0000, v107
	v_pk_fma_f32 v[2:3], v[138:139], v[140:141], v[2:3]
	s_branch .Lssdc0_tail
.Lssdc0_slow:
	s_and_saveexec_b64 s[2:3], s[6:7]
	s_cbranch_execz .LBB0_980
	global_load_dwordx4 v[12:15], v[10:11], off offset:2304
	global_load_dwordx4 v[22:25], v[8:9], off offset:1552
	global_load_dwordx4 v[26:29], v[8:9], off offset:1536
	s_waitcnt vmcnt(2)
	v_lshlrev_b32_e32 v18, 16, v12
	v_and_b32_e32 v19, 0xffff0000, v12
	v_lshlrev_b32_e32 v12, 16, v13
	v_and_b32_e32 v13, 0xffff0000, v13
	s_waitcnt vmcnt(0)
	v_pk_fma_f32 v[6:7], v[28:29], v[12:13], v[6:7]
	v_lshlrev_b32_e32 v12, 16, v14
	v_and_b32_e32 v13, 0xffff0000, v14
	v_pk_fma_f32 v[0:1], v[22:23], v[12:13], v[0:1]
	v_lshlrev_b32_e32 v12, 16, v15
	v_and_b32_e32 v13, 0xffff0000, v15
	v_pk_fma_f32 v[4:5], v[26:27], v[18:19], v[4:5]
	v_pk_fma_f32 v[2:3], v[24:25], v[12:13], v[2:3]

.Lssdc0_tail:
	s_waitcnt vmcnt(0)
	v_mul_f32_e32 v18, 0xbfb8aa3b, v4
	v_exp_f32_e32 v18, v18
	v_ashrrev_i32_e32 v65, 31, v64
	v_lshlrev_b64 v[20:21], 8, v[64:65]
	s_andn2_b64 vcc, exec, s[72:73]
	v_add_f32_e32 v18, 1.0, v18
	v_rcp_f32_e32 v18, v18
	s_nop 0
	v_mul_f32_e32 v4, v4, v18
	v_mul_f32_e32 v18, 0xbfb8aa3b, v5
	v_exp_f32_e32 v18, v18
	s_nop 0
	v_add_f32_e32 v18, 1.0, v18
	v_rcp_f32_e32 v18, v18
	s_nop 0
	v_mul_f32_e32 v5, v5, v18
	v_mul_f32_e32 v18, 0xbfb8aa3b, v6
	v_exp_f32_e32 v18, v18
	v_cvt_pk_bf16_f32 v48, v4, v5
	v_add_f32_e32 v18, 1.0, v18
	v_rcp_f32_e32 v18, v18
	s_nop 0
	v_mul_f32_e32 v6, v6, v18
	v_mul_f32_e32 v18, 0xbfb8aa3b, v7
	v_exp_f32_e32 v18, v18
	s_nop 0
	v_add_f32_e32 v18, 1.0, v18
	v_rcp_f32_e32 v18, v18
	s_nop 0
	v_mul_f32_e32 v7, v7, v18
	v_mul_f32_e32 v18, 0xbfb8aa3b, v0
	v_exp_f32_e32 v18, v18
	v_cvt_pk_bf16_f32 v49, v6, v7
	v_add_f32_e32 v18, 1.0, v18
	v_rcp_f32_e32 v18, v18
	s_nop 0
	v_mul_f32_e32 v0, v0, v18
	v_mul_f32_e32 v18, 0xbfb8aa3b, v1
	v_exp_f32_e32 v18, v18
	s_nop 0
	v_add_f32_e32 v18, 1.0, v18
	v_rcp_f32_e32 v18, v18
	s_nop 0
	v_mul_f32_e32 v1, v1, v18
	v_mul_f32_e32 v18, 0xbfb8aa3b, v2
	v_exp_f32_e32 v18, v18
	v_cvt_pk_bf16_f32 v50, v0, v1
	v_cndmask_b32_e64 v0, 0, 1, s[72:73]
	v_cmp_ne_u32_e64 s[14:15], 1, v0
	v_add_f32_e32 v18, 1.0, v18
	v_rcp_f32_e32 v18, v18
	s_nop 0
	v_mul_f32_e32 v2, v2, v18
	v_mul_f32_e32 v18, 0xbfb8aa3b, v3
	v_exp_f32_e32 v18, v18
	s_nop 0
	v_add_f32_e32 v18, 1.0, v18
	v_rcp_f32_e32 v18, v18
	s_nop 0
	v_mul_f32_e32 v3, v3, v18
	v_cvt_pk_bf16_f32 v51, v2, v3
	v_lshlrev_b32_e32 v18, 1, v70
	s_cbranch_vccnz .LBB0_988
	v_lshl_add_u64 v[0:1], s[58:59], 0, v[20:21]
	s_lshl_b32 s52, s5, 1
	v_lshl_add_u64 v[0:1], v[0:1], 0, s[52:53]
	v_mov_b32_e32 v19, v169
	v_lshl_add_u64 v[0:1], v[0:1], 0, v[18:19]
	global_store_dwordx4 v[0:1], v[48:51], off
.LBB0_988:
	v_lshl_add_u64 v[22:23], s[74:75], 0, v[168:169]
	global_load_dwordx4 v[0:3], v[22:23], off offset:1616
	global_load_dwordx4 v[4:7], v[22:23], off offset:1600
	s_cmp_eq_u64 s[6:7], -1
	s_cbranch_scc0 .Lssdc1_slow
	s_mov_b64 s[0:1], 0x1000
	v_lshl_add_u64 v[140:141], v[8:9], 0, s[0:1]
	global_load_dwordx4 v[92:95], v[10:11], off offset:2336
	global_load_dwordx4 v[96:99], v[12:13], off offset:2336
	global_load_dwordx4 v[100:103], v[14:15], off offset:2336
	global_load_dwordx4 v[104:107], v[16:17], off offset:2336
	global_load_dwordx4 v[108:111], v[8:9], off offset:1600
	global_load_dwordx4 v[112:115], v[8:9], off offset:1616
	global_load_dwordx4 v[116:119], v[8:9], off offset:3648
	global_load_dwordx4 v[120:123], v[8:9], off offset:3664
	global_load_dwordx4 v[124:127], v[140:141], off offset:1600
	global_load_dwordx4 v[128:131], v[140:141], off offset:1616
	global_load_dwordx4 v[132:135], v[140:141], off offset:3648
	global_load_dwordx4 v[136:139], v[140:141], off offset:3664
	s_waitcnt vmcnt(0)
	v_lshlrev_b32_e32 v140, 16, v92
	v_and_b32_e32 v141, 0xffff0000, v92
	v_pk_fma_f32 v[4:5], v[108:109], v[140:141], v[4:5]
	v_lshlrev_b32_e32 v140, 16, v93
	v_and_b32_e32 v141, 0xffff0000, v93
	v_pk_fma_f32 v[6:7], v[110:111], v[140:141], v[6:7]
	v_lshlrev_b32_e32 v140, 16, v94
	v_and_b32_e32 v141, 0xffff0000, v94
	v_pk_fma_f32 v[0:1], v[112:113], v[140:141], v[0:1]
	v_lshlrev_b32_e32 v140, 16, v95
	v_and_b32_e32 v141, 0xffff0000, v95
	v_pk_fma_f32 v[2:3], v[114:115], v[140:141], v[2:3]
	v_lshlrev_b32_e32 v140, 16, v96
	v_and_b32_e32 v141, 0xffff0000, v96
	v_pk_fma_f32 v[4:5], v[116:117], v[140:141], v[4:5]
	v_lshlrev_b32_e32 v140, 16, v97
	v_and_b32_e32 v141, 0xffff0000, v97
	v_pk_fma_f32 v[6:7], v[118:119], v[140:141], v[6:7]
	v_lshlrev_b32_e32 v140, 16, v98
	v_and_b32_e32 v141, 0xffff0000, v98
	v_pk_fma_f32 v[0:1], v[120:121], v[140:141], v[0:1]
	v_lshlrev_b32_e32 v140, 16, v99
	v_and_b32_e32 v141, 0xffff0000, v99
	v_pk_fma_f32 v[2:3], v[122:123], v[140:141], v[2:3]
	v_lshlrev_b32_e32 v140, 16, v100
	v_and_b32_e32 v141, 0xffff0000, v100
	v_pk_fma_f32 v[4:5], v[124:125], v[140:141], v[4:5]
	v_lshlrev_b32_e32 v140, 16, v101
	v_and_b32_e32 v141, 0xffff0000, v101
	v_pk_fma_f32 v[6:7], v[126:127], v[140:141], v[6:7]
	v_lshlrev_b32_e32 v140, 16, v102
	v_and_b32_e32 v141, 0xffff0000, v102
	v_pk_fma_f32 v[0:1], v[128:129], v[140:141], v[0:1]
	v_lshlrev_b32_e32 v140, 16, v103
	v_and_b32_e32 v141, 0xffff0000, v103
	v_pk_fma_f32 v[2:3], v[130:131], v[140:141], v[2:3]
	v_lshlrev_b32_e32 v140, 16, v104
	v_and_b32_e32 v141, 0xffff0000, v104
	v_pk_fma_f32 v[4:5], v[132:133], v[140:141], v[4:5]
	v_lshlrev_b32_e32 v140, 16, v105
	v_and_b32_e32 v141, 0xffff0000, v105
	v_pk_fma_f32 v[6:7], v[134:135], v[140:141], v[6:7]
	v_lshlrev_b32_e32 v140, 16, v106
	v_and_b32_e32 v141, 0xffff0000, v106
	v_pk_fma_f32 v[0:1], v[136:137], v[140:141], v[0:1]
	v_lshlrev_b32_e32 v140, 16, v107
	v_and_b32_e32 v141, 0xffff0000, v107
	v_pk_fma_f32 v[2:3], v[138:139], v[140:141], v[2:3]
	s_branch .Lssdc1_tail
.Lssdc1_slow:
	s_and_saveexec_b64 s[2:3], s[6:7]
	s_cbranch_execz .LBB0_990
	global_load_dwordx4 v[24:27], v[10:11], off offset:2336
	global_load_dwordx4 v[28:31], v[8:9], off offset:1616
	global_load_dwordx4 v[34:37], v[8:9], off offset:1600
	s_waitcnt vmcnt(2)
	v_lshlrev_b32_e32 v38, 16, v24
	v_and_b32_e32 v39, 0xffff0000, v24
	v_lshlrev_b32_e32 v24, 16, v25
	v_and_b32_e32 v25, 0xffff0000, v25
	s_waitcnt vmcnt(0)
	v_pk_fma_f32 v[6:7], v[36:37], v[24:25], v[6:7]
	v_lshlrev_b32_e32 v24, 16, v26
	v_and_b32_e32 v25, 0xffff0000, v26
	v_pk_fma_f32 v[0:1], v[28:29], v[24:25], v[0:1]
	v_lshlrev_b32_e32 v24, 16, v27
	v_and_b32_e32 v25, 0xffff0000, v27
	v_pk_fma_f32 v[4:5], v[34:35], v[38:39], v[4:5]
	v_pk_fma_f32 v[2:3], v[30:31], v[24:25], v[2:3]

.Lssdc1_tail:
	s_waitcnt vmcnt(0)
	v_mul_f32_e32 v19, 0xbfb8aa3b, v4
	v_exp_f32_e32 v19, v19
	s_and_b64 vcc, exec, s[14:15]
	v_lshl_add_u64 v[20:21], s[82:83], 0, v[20:21]
	v_add_f32_e32 v19, 1.0, v19
	v_rcp_f32_e32 v19, v19
	s_nop 0
	v_mul_f32_e32 v4, v4, v19
	v_mul_f32_e32 v19, 0xbfb8aa3b, v5
	v_exp_f32_e32 v19, v19
	s_nop 0
	v_add_f32_e32 v19, 1.0, v19
	v_rcp_f32_e32 v19, v19
	s_nop 0
	v_mul_f32_e32 v5, v5, v19
	v_mul_f32_e32 v19, 0xbfb8aa3b, v6
	v_exp_f32_e32 v19, v19
	v_cvt_pk_bf16_f32 v52, v4, v5
	v_add_f32_e32 v19, 1.0, v19
	v_rcp_f32_e32 v19, v19
	s_nop 0
	v_mul_f32_e32 v6, v6, v19
	v_mul_f32_e32 v19, 0xbfb8aa3b, v7
	v_exp_f32_e32 v19, v19
	s_nop 0
	v_add_f32_e32 v19, 1.0, v19
	v_rcp_f32_e32 v19, v19
	s_nop 0
	v_mul_f32_e32 v7, v7, v19
	v_mul_f32_e32 v19, 0xbfb8aa3b, v0
	v_exp_f32_e32 v19, v19
	v_cvt_pk_bf16_f32 v53, v6, v7
	v_add_f32_e32 v19, 1.0, v19
	v_rcp_f32_e32 v19, v19
	s_nop 0
	v_mul_f32_e32 v0, v0, v19
	v_mul_f32_e32 v19, 0xbfb8aa3b, v1
	v_exp_f32_e32 v19, v19
	s_nop 0
	v_add_f32_e32 v19, 1.0, v19
	v_rcp_f32_e32 v19, v19
	s_nop 0
	v_mul_f32_e32 v1, v1, v19
	v_mul_f32_e32 v19, 0xbfb8aa3b, v2
	v_exp_f32_e32 v19, v19
	v_cvt_pk_bf16_f32 v54, v0, v1
	v_add_f32_e32 v19, 1.0, v19
	v_rcp_f32_e32 v19, v19
	s_nop 0
	v_mul_f32_e32 v2, v2, v19
	v_mul_f32_e32 v19, 0xbfb8aa3b, v3
	v_exp_f32_e32 v19, v19
	s_nop 0
	v_add_f32_e32 v19, 1.0, v19
	v_rcp_f32_e32 v19, v19
	s_nop 0
	v_mul_f32_e32 v3, v3, v19
	v_cvt_pk_bf16_f32 v55, v2, v3
	s_cbranch_vccz .LBB0_1048
	global_load_dwordx4 v[0:3], v[22:23], off offset:1680
	global_load_dwordx4 v[4:7], v[22:23], off offset:1664
	s_cmp_eq_u64 s[6:7], -1
	s_cbranch_scc1 .Lssdc2_fast
	s_and_saveexec_b64 s[2:3], s[6:7]
	s_cbranch_execnz .LBB0_1049

.Lssdc2_tail:
	s_waitcnt vmcnt(0)
	v_mul_f32_e32 v19, 0xbfb8aa3b, v4
	v_exp_f32_e32 v19, v19
	s_and_b64 vcc, exec, s[14:15]
	v_add_f32_e32 v19, 1.0, v19
	v_rcp_f32_e32 v19, v19
	s_nop 0
	v_mul_f32_e32 v4, v4, v19
	v_mul_f32_e32 v19, 0xbfb8aa3b, v5
	v_exp_f32_e32 v19, v19
	s_nop 0
	v_add_f32_e32 v19, 1.0, v19
	v_rcp_f32_e32 v19, v19
	s_nop 0
	v_mul_f32_e32 v5, v5, v19
	v_mul_f32_e32 v19, 0xbfb8aa3b, v6
	v_exp_f32_e32 v19, v19
	v_cvt_pk_bf16_f32 v56, v4, v5
	v_add_f32_e32 v19, 1.0, v19
	v_rcp_f32_e32 v19, v19
	s_nop 0
	v_mul_f32_e32 v6, v6, v19
	v_mul_f32_e32 v19, 0xbfb8aa3b, v7
	v_exp_f32_e32 v19, v19
	s_nop 0
	v_add_f32_e32 v19, 1.0, v19
	v_rcp_f32_e32 v19, v19
	s_nop 0
	v_mul_f32_e32 v7, v7, v19
	v_mul_f32_e32 v19, 0xbfb8aa3b, v0
	v_exp_f32_e32 v19, v19
	v_cvt_pk_bf16_f32 v57, v6, v7
	v_add_f32_e32 v19, 1.0, v19
	v_rcp_f32_e32 v19, v19
	s_nop 0
	v_mul_f32_e32 v0, v0, v19
	v_mul_f32_e32 v19, 0xbfb8aa3b, v1
	v_exp_f32_e32 v19, v19
	s_nop 0
	v_add_f32_e32 v19, 1.0, v19
	v_rcp_f32_e32 v19, v19
	s_nop 0
	v_mul_f32_e32 v1, v1, v19
	v_mul_f32_e32 v19, 0xbfb8aa3b, v2
	v_exp_f32_e32 v19, v19
	v_cvt_pk_bf16_f32 v58, v0, v1
	v_add_f32_e32 v19, 1.0, v19
	v_rcp_f32_e32 v19, v19
	s_nop 0
	v_mul_f32_e32 v2, v2, v19
	v_mul_f32_e32 v19, 0xbfb8aa3b, v3
	v_exp_f32_e32 v19, v19
	s_nop 0
	v_add_f32_e32 v19, 1.0, v19
	v_rcp_f32_e32 v19, v19
	s_nop 0
	v_mul_f32_e32 v3, v3, v19
	v_cvt_pk_bf16_f32 v59, v2, v3
	s_cbranch_vccz .LBB0_1050
	global_load_dwordx4 v[0:3], v[22:23], off offset:1744
	global_load_dwordx4 v[4:7], v[22:23], off offset:1728
	s_cmp_eq_u64 s[6:7], -1
	s_cbranch_scc1 .Lssdc3_fast
	s_and_saveexec_b64 s[2:3], s[6:7]
	s_cbranch_execnz .LBB0_1051

.Lssdc3_tail:
	s_waitcnt vmcnt(0)
	v_mul_f32_e32 v8, 0xbfb8aa3b, v4
	v_exp_f32_e32 v8, v8
	s_and_b64 vcc, exec, s[14:15]
	v_add_f32_e32 v8, 1.0, v8
	v_rcp_f32_e32 v8, v8
	s_nop 0
	v_mul_f32_e32 v4, v4, v8
	v_mul_f32_e32 v8, 0xbfb8aa3b, v5
	v_exp_f32_e32 v8, v8
	s_nop 0
	v_add_f32_e32 v8, 1.0, v8
	v_rcp_f32_e32 v8, v8
	s_nop 0
	v_mul_f32_e32 v5, v5, v8
	v_mul_f32_e32 v8, 0xbfb8aa3b, v6
	v_exp_f32_e32 v8, v8
	v_cvt_pk_bf16_f32 v60, v4, v5
	v_add_f32_e32 v8, 1.0, v8
	v_rcp_f32_e32 v8, v8
	s_nop 0
	v_mul_f32_e32 v6, v6, v8
	v_mul_f32_e32 v8, 0xbfb8aa3b, v7
	v_exp_f32_e32 v8, v8
	s_nop 0
	v_add_f32_e32 v8, 1.0, v8
	v_rcp_f32_e32 v8, v8
	s_nop 0
	v_mul_f32_e32 v7, v7, v8
	v_mul_f32_e32 v8, 0xbfb8aa3b, v0
	v_exp_f32_e32 v8, v8
	v_cvt_pk_bf16_f32 v61, v6, v7
	v_add_f32_e32 v8, 1.0, v8
	v_rcp_f32_e32 v8, v8
	s_nop 0
	v_mul_f32_e32 v0, v0, v8
	v_mul_f32_e32 v8, 0xbfb8aa3b, v1
	v_exp_f32_e32 v8, v8
	s_nop 0
	v_add_f32_e32 v8, 1.0, v8
	v_rcp_f32_e32 v8, v8
	s_nop 0
	v_mul_f32_e32 v1, v1, v8
	v_mul_f32_e32 v8, 0xbfb8aa3b, v2
	v_exp_f32_e32 v8, v8
	v_cvt_pk_bf16_f32 v62, v0, v1
	v_add_f32_e32 v8, 1.0, v8
	v_rcp_f32_e32 v8, v8
	s_nop 0
	v_mul_f32_e32 v2, v2, v8
	v_mul_f32_e32 v8, 0xbfb8aa3b, v3
	v_exp_f32_e32 v8, v8
	s_nop 0
	v_add_f32_e32 v8, 1.0, v8
	v_rcp_f32_e32 v8, v8
	s_nop 0
	v_mul_f32_e32 v3, v3, v8
	v_cvt_pk_bf16_f32 v63, v2, v3
	s_cbranch_vccnz .LBB0_1014
	s_lshl_b32 s52, s5, 1
	v_lshl_add_u64 v[0:1], v[20:21], 0, s[52:53]
	v_mov_b32_e32 v19, v169
	v_lshl_add_u64 v[0:1], v[0:1], 0, v[18:19]
	v_add_co_u32_e32 v0, vcc, 0x107b9000, v0
	s_nop 1
	v_addc_co_u32_e32 v1, vcc, 0, v1, vcc
	global_store_dwordx4 v[0:1], v[60:63], off offset:96

.LBB0_1048:
	s_lshl_b32 s52, s5, 1
	v_lshl_add_u64 v[0:1], v[20:21], 0, s[52:53]
	v_mov_b32_e32 v19, v169
	v_lshl_add_u64 v[0:1], v[0:1], 0, v[18:19]
	v_add_co_u32_e32 v0, vcc, 0x107b9000, v0
	s_nop 1
	v_addc_co_u32_e32 v1, vcc, 0, v1, vcc
	global_store_dwordx4 v[0:1], v[52:55], off offset:32
	global_load_dwordx4 v[0:3], v[22:23], off offset:1680
	s_nop 0
	global_load_dwordx4 v[4:7], v[22:23], off offset:1664
	s_cmp_eq_u64 s[6:7], -1
	s_cbranch_scc1 .Lssdc2_fast
	s_and_saveexec_b64 s[2:3], s[6:7]
	s_cbranch_execz .LBB0_998

.LBB0_1050:
	s_lshl_b32 s52, s5, 1
	v_lshl_add_u64 v[0:1], v[20:21], 0, s[52:53]
	v_mov_b32_e32 v19, v169
	v_lshl_add_u64 v[0:1], v[0:1], 0, v[18:19]
	v_add_co_u32_e32 v0, vcc, 0x107b9000, v0
	s_nop 1
	v_addc_co_u32_e32 v1, vcc, 0, v1, vcc
	global_store_dwordx4 v[0:1], v[56:59], off offset:64
	global_load_dwordx4 v[0:3], v[22:23], off offset:1744
	s_nop 0
	global_load_dwordx4 v[4:7], v[22:23], off offset:1728
	s_cmp_eq_u64 s[6:7], -1
	s_cbranch_scc1 .Lssdc3_fast
	s_and_saveexec_b64 s[2:3], s[6:7]
	s_cbranch_execz .LBB0_1006

.Lssdc2_fast:
	s_mov_b64 s[0:1], 0x1000
	v_lshl_add_u64 v[140:141], v[8:9], 0, s[0:1]
	global_load_dwordx4 v[92:95], v[10:11], off offset:2368
	global_load_dwordx4 v[96:99], v[12:13], off offset:2368
	global_load_dwordx4 v[100:103], v[14:15], off offset:2368
	global_load_dwordx4 v[104:107], v[16:17], off offset:2368
	global_load_dwordx4 v[108:111], v[8:9], off offset:1664
	global_load_dwordx4 v[112:115], v[8:9], off offset:1680
	global_load_dwordx4 v[116:119], v[8:9], off offset:3712
	global_load_dwordx4 v[120:123], v[8:9], off offset:3728
	global_load_dwordx4 v[124:127], v[140:141], off offset:1664
	global_load_dwordx4 v[128:131], v[140:141], off offset:1680
	global_load_dwordx4 v[132:135], v[140:141], off offset:3712
	global_load_dwordx4 v[136:139], v[140:141], off offset:3728
	s_waitcnt vmcnt(0)
	v_lshlrev_b32_e32 v140, 16, v92
	v_and_b32_e32 v141, 0xffff0000, v92
	v_pk_fma_f32 v[4:5], v[108:109], v[140:141], v[4:5]
	v_lshlrev_b32_e32 v140, 16, v93
	v_and_b32_e32 v141, 0xffff0000, v93
	v_pk_fma_f32 v[6:7], v[110:111], v[140:141], v[6:7]
	v_lshlrev_b32_e32 v140, 16, v94
	v_and_b32_e32 v141, 0xffff0000, v94
	v_pk_fma_f32 v[0:1], v[112:113], v[140:141], v[0:1]
	v_lshlrev_b32_e32 v140, 16, v95
	v_and_b32_e32 v141, 0xffff0000, v95
	v_pk_fma_f32 v[2:3], v[114:115], v[140:141], v[2:3]
	v_lshlrev_b32_e32 v140, 16, v96
	v_and_b32_e32 v141, 0xffff0000, v96
	v_pk_fma_f32 v[4:5], v[116:117], v[140:141], v[4:5]
	v_lshlrev_b32_e32 v140, 16, v97
	v_and_b32_e32 v141, 0xffff0000, v97
	v_pk_fma_f32 v[6:7], v[118:119], v[140:141], v[6:7]
	v_lshlrev_b32_e32 v140, 16, v98
	v_and_b32_e32 v141, 0xffff0000, v98
	v_pk_fma_f32 v[0:1], v[120:121], v[140:141], v[0:1]
	v_lshlrev_b32_e32 v140, 16, v99
	v_and_b32_e32 v141, 0xffff0000, v99
	v_pk_fma_f32 v[2:3], v[122:123], v[140:141], v[2:3]
	v_lshlrev_b32_e32 v140, 16, v100
	v_and_b32_e32 v141, 0xffff0000, v100
	v_pk_fma_f32 v[4:5], v[124:125], v[140:141], v[4:5]
	v_lshlrev_b32_e32 v140, 16, v101
	v_and_b32_e32 v141, 0xffff0000, v101
	v_pk_fma_f32 v[6:7], v[126:127], v[140:141], v[6:7]
	v_lshlrev_b32_e32 v140, 16, v102
	v_and_b32_e32 v141, 0xffff0000, v102
	v_pk_fma_f32 v[0:1], v[128:129], v[140:141], v[0:1]
	v_lshlrev_b32_e32 v140, 16, v103
	v_and_b32_e32 v141, 0xffff0000, v103
	v_pk_fma_f32 v[2:3], v[130:131], v[140:141], v[2:3]
	v_lshlrev_b32_e32 v140, 16, v104
	v_and_b32_e32 v141, 0xffff0000, v104
	v_pk_fma_f32 v[4:5], v[132:133], v[140:141], v[4:5]
	v_lshlrev_b32_e32 v140, 16, v105
	v_and_b32_e32 v141, 0xffff0000, v105
	v_pk_fma_f32 v[6:7], v[134:135], v[140:141], v[6:7]
	v_lshlrev_b32_e32 v140, 16, v106
	v_and_b32_e32 v141, 0xffff0000, v106
	v_pk_fma_f32 v[0:1], v[136:137], v[140:141], v[0:1]
	v_lshlrev_b32_e32 v140, 16, v107
	v_and_b32_e32 v141, 0xffff0000, v107
	v_pk_fma_f32 v[2:3], v[138:139], v[140:141], v[2:3]
	s_branch .Lssdc2_tail
.Lssdc3_fast:
	s_mov_b64 s[0:1], 0x1000
	v_lshl_add_u64 v[140:141], v[8:9], 0, s[0:1]
	global_load_dwordx4 v[92:95], v[10:11], off offset:2400
	global_load_dwordx4 v[96:99], v[12:13], off offset:2400
	global_load_dwordx4 v[100:103], v[14:15], off offset:2400
	global_load_dwordx4 v[104:107], v[16:17], off offset:2400
	global_load_dwordx4 v[108:111], v[8:9], off offset:1728
	global_load_dwordx4 v[112:115], v[8:9], off offset:1744
	global_load_dwordx4 v[116:119], v[8:9], off offset:3776
	global_load_dwordx4 v[120:123], v[8:9], off offset:3792
	global_load_dwordx4 v[124:127], v[140:141], off offset:1728
	global_load_dwordx4 v[128:131], v[140:141], off offset:1744
	global_load_dwordx4 v[132:135], v[140:141], off offset:3776
	global_load_dwordx4 v[136:139], v[140:141], off offset:3792
	s_waitcnt vmcnt(0)
	v_lshlrev_b32_e32 v140, 16, v92
	v_and_b32_e32 v141, 0xffff0000, v92
	v_pk_fma_f32 v[4:5], v[108:109], v[140:141], v[4:5]
	v_lshlrev_b32_e32 v140, 16, v93
	v_and_b32_e32 v141, 0xffff0000, v93
	v_pk_fma_f32 v[6:7], v[110:111], v[140:141], v[6:7]
	v_lshlrev_b32_e32 v140, 16, v94
	v_and_b32_e32 v141, 0xffff0000, v94
	v_pk_fma_f32 v[0:1], v[112:113], v[140:141], v[0:1]
	v_lshlrev_b32_e32 v140, 16, v95
	v_and_b32_e32 v141, 0xffff0000, v95
	v_pk_fma_f32 v[2:3], v[114:115], v[140:141], v[2:3]
	v_lshlrev_b32_e32 v140, 16, v96
	v_and_b32_e32 v141, 0xffff0000, v96
	v_pk_fma_f32 v[4:5], v[116:117], v[140:141], v[4:5]
	v_lshlrev_b32_e32 v140, 16, v97
	v_and_b32_e32 v141, 0xffff0000, v97
	v_pk_fma_f32 v[6:7], v[118:119], v[140:141], v[6:7]
	v_lshlrev_b32_e32 v140, 16, v98
	v_and_b32_e32 v141, 0xffff0000, v98
	v_pk_fma_f32 v[0:1], v[120:121], v[140:141], v[0:1]
	v_lshlrev_b32_e32 v140, 16, v99
	v_and_b32_e32 v141, 0xffff0000, v99
	v_pk_fma_f32 v[2:3], v[122:123], v[140:141], v[2:3]
	v_lshlrev_b32_e32 v140, 16, v100
	v_and_b32_e32 v141, 0xffff0000, v100
	v_pk_fma_f32 v[4:5], v[124:125], v[140:141], v[4:5]
	v_lshlrev_b32_e32 v140, 16, v101
	v_and_b32_e32 v141, 0xffff0000, v101
	v_pk_fma_f32 v[6:7], v[126:127], v[140:141], v[6:7]
	v_lshlrev_b32_e32 v140, 16, v102
	v_and_b32_e32 v141, 0xffff0000, v102
	v_pk_fma_f32 v[0:1], v[128:129], v[140:141], v[0:1]
	v_lshlrev_b32_e32 v140, 16, v103
	v_and_b32_e32 v141, 0xffff0000, v103
	v_pk_fma_f32 v[2:3], v[130:131], v[140:141], v[2:3]
	v_lshlrev_b32_e32 v140, 16, v104
	v_and_b32_e32 v141, 0xffff0000, v104
	v_pk_fma_f32 v[4:5], v[132:133], v[140:141], v[4:5]
	v_lshlrev_b32_e32 v140, 16, v105
	v_and_b32_e32 v141, 0xffff0000, v105
	v_pk_fma_f32 v[6:7], v[134:135], v[140:141], v[6:7]
	v_lshlrev_b32_e32 v140, 16, v106
	v_and_b32_e32 v141, 0xffff0000, v106
	v_pk_fma_f32 v[0:1], v[136:137], v[140:141], v[0:1]
	v_lshlrev_b32_e32 v140, 16, v107
	v_and_b32_e32 v141, 0xffff0000, v107
	v_pk_fma_f32 v[2:3], v[138:139], v[140:141], v[2:3]
	s_branch .Lssdc3_tail
